# helpers prefetch K,Q rows + TM,ATT tiles (GDN) and HQ rows (HGRN) only
# speedup vs baseline: 1.0151x; 1.0076x over previous
.LBB0_320:
	v_lshlrev_b64 v[8:9], 1, v[2:3]
	s_lshl_b64 s[18:19], s[2:3], 14
	v_readlane_b32 s36, v253, 29
	v_lshl_add_u64 v[10:11], s[60:61], 0, v[8:9]
	global_load_dwordx4 v[4:7], v[10:11], off
	v_readlane_b32 s37, v253, 30
	v_readlane_b32 s38, v253, 31
	v_readlane_b32 s39, v253, 32
	s_add_u32 s34, s36, s18
	v_lshl_add_u64 v[10:11], v[10:11], 0, s[12:13]
	global_load_dwordx4 v[4:7], v[10:11], off
	v_lshl_add_u64 v[8:9], s[70:71], 0, v[8:9]
	s_addc_u32 s35, s37, s19
	v_readlane_b32 s36, v253, 41
	global_load_dwordx4 v[4:7], v[8:9], off
	v_lshl_add_u64 v[8:9], v[8:9], 0, s[12:13]
	v_mov_b32_e32 v13, v3
	v_readlane_b32 s48, v253, 53
	global_load_dwordx4 v[4:7], v[8:9], off
	v_lshl_add_u64 v[8:9], s[34:35], 0, v[12:13]
	v_readlane_b32 s49, v253, 54
	s_add_u32 s18, s48, s18
	s_nop 0
	v_lshl_add_u64 v[8:9], v[8:9], 0, s[14:15]
	s_addc_u32 s19, s49, s19
	s_lshl_b64 s[16:17], s[16:17], 13
	s_nop 0
	v_lshl_add_u64 v[8:9], s[18:19], 0, v[12:13]
	s_add_u32 s18, s0, s16
	s_addc_u32 s19, s1, s17
	s_nop 0
	v_lshl_add_u64 v[8:9], v[8:9], 0, s[14:15]
	s_add_u32 s16, s88, s16
	v_readlane_b32 s2, v253, 33
	s_nop 0
	v_lshl_add_u64 v[8:9], s[18:19], 0, v[12:13]
	s_addc_u32 s17, s2, s17
	global_load_dwordx4 v[4:7], v[8:9], off
	v_lshl_add_u64 v[8:9], s[16:17], 0, v[12:13]
	global_load_dwordx4 v[4:7], v[8:9], off
	v_readlane_b32 s37, v253, 42
	v_mov_b64_e32 v[10:11], v[6:7]
	v_mov_b64_e32 v[8:9], v[4:5]
	v_readlane_b32 s38, v253, 43
	v_readlane_b32 s39, v253, 44
	v_readlane_b32 s40, v253, 45
	v_readlane_b32 s41, v253, 46
	v_readlane_b32 s42, v253, 47
	v_readlane_b32 s43, v253, 48
	v_readlane_b32 s44, v253, 49
	v_readlane_b32 s45, v253, 50
	v_readlane_b32 s46, v253, 51
	v_readlane_b32 s47, v253, 52
	v_readlane_b32 s50, v253, 55
	v_readlane_b32 s51, v253, 56
	s_add_i32 s22, s22, 1
	s_cmp_eq_u32 s22, 64
	s_cbranch_scc1 .LBB0_322
